# speedup vs baseline: 1.0102x; 1.0073x over previous
; template <int EPI, int AMAP, int KOFFMODE, int K>
; __device__ __forceinline__ void gemm_phase(unsigned char* smem, const bf16_t* A, int lda, const bf16_t* Bt, int NT, const EpiArgs& ea) {
;     ...
;         for (int kt = 0; kt < nk; ++kt) {
;             if (kt + 1 < nk) GEMM_DMA(m0, n0, kt + 1, cur ^ 1);
;             else if (have_next) GEMM_DMA(m0n, n0n, 0, cur ^ 1);
;             const unsigned char* Ac = smem + cur * STGB + (wm * 128 + l31) * 128;
;             const unsigned char* Bc = smem + cur * STGB + 32768 + (wn * 64 + l31) * 128;
;             bf16x8 fa[2][4], fb[2][2];
;             fb[0][0] = *(const bf16x8*)(Bc + (((0) ^ yz) & 7) * 16);
;             fb[0][1] = *(const bf16x8*)(Bc + 32 * 128 + (((0) ^ yz) & 7) * 16);
; #pragma unroll
;             for (int i = 0; i < 4; ++i) fa[0][i] = *(const bf16x8*)(Ac + i * 32 * 128 + (((0) ^ yz) & 7) * 16);
; #pragma unroll
;             for (int s = 0; s < 4; ++s) {
;                 if (s < 3) {
;                     const int o_ = (((2 * (s + 1)) ^ yz) & 7) * 16;
;                     fb[(s + 1) & 1][0] = *(const bf16x8*)(Bc + o_);
;                     fb[(s + 1) & 1][1] = *(const bf16x8*)(Bc + 32 * 128 + o_);
; #pragma unroll
;                     for (int i = 0; i < 4; ++i) fa[(s + 1) & 1][i] = *(const bf16x8*)(Ac + i * 32 * 128 + o_);
;                 }
; #pragma unroll
;                 for (int i = 0; i < 4; ++i) {
;                     acc[i][0] = __builtin_amdgcn_mfma_f32_32x32x16_bf16(fa[s & 1][i], fb[s & 1][0], acc[i][0], 0, 0, 0);
;                     acc[i][1] = __builtin_amdgcn_mfma_f32_32x32x16_bf16(fa[s & 1][i], fb[s & 1][1], acc[i][1], 0, 0, 0);
;                 }
;                 __builtin_amdgcn_sched_barrier(0);
;             }
;             if (kt + 1 < nk) asm volatile("s_waitcnt vmcnt(0)" ::: "memory");
;             __builtin_amdgcn_s_barrier();
.LBB0_461:
	s_mov_b32 s9, s13
	s_lshl_b32 s13, s9, 16
	s_xor_b32 s12, s13, 0x10000
	v_readfirstlane_b32 vcc_lo, v143
	s_nop 0
	s_add_u32 vcc_lo, vcc_lo, s12
	s_add_u32 s14, s4, 0xb240080
	s_addc_u32 s15, s5, 0
	s_mov_b32 m0, vcc_lo
	v_lshl_add_u64 v[164:165], v[136:137], 0, s[14:15]
	global_load_lds_dwordx4 v[164:165], off
	s_add_u32 s14, s4, 0xb270080
	s_addc_u32 s15, s5, 0
	s_add_u32 m0, vcc_lo, 0x2000
	v_lshl_add_u64 v[164:165], v[136:137], 0, s[14:15]
	global_load_lds_dwordx4 v[164:165], off
	s_add_u32 s14, s4, 0xb2a0080
	s_addc_u32 s15, s5, 0
	s_add_u32 m0, vcc_lo, 0x4000
	v_lshl_add_u64 v[164:165], v[136:137], 0, s[14:15]
	global_load_lds_dwordx4 v[164:165], off
	s_add_u32 s14, s4, 0xb2d0080
	s_addc_u32 s15, s5, 0
	s_add_u32 m0, vcc_lo, 0x6000
	v_lshl_add_u64 v[164:165], v[136:137], 0, s[14:15]
	global_load_lds_dwordx4 v[164:165], off
	s_add_u32 s14, s4, 0xb00080
	s_addc_u32 s15, s5, 0
	s_add_u32 m0, vcc_lo, 0x8000
	v_lshl_add_u64 v[164:165], v[138:139], 0, s[14:15]
	global_load_lds_dwordx4 v[164:165], off
	s_add_u32 s14, s4, 0xb30080
	s_addc_u32 s15, s5, 0
	s_add_u32 m0, vcc_lo, 0xa000
	v_lshl_add_u64 v[164:165], v[138:139], 0, s[14:15]
	global_load_lds_dwordx4 v[164:165], off
	s_add_u32 s14, s4, 0xb60080
	s_addc_u32 s15, s5, 0
	s_add_u32 m0, vcc_lo, 0xc000
	v_lshl_add_u64 v[164:165], v[138:139], 0, s[14:15]
	global_load_lds_dwordx4 v[164:165], off
	s_add_u32 s14, s4, 0xb90080
	s_addc_u32 s15, s5, 0
	s_add_u32 m0, vcc_lo, 0xe000
	v_lshl_add_u64 v[164:165], v[138:139], 0, s[14:15]
	global_load_lds_dwordx4 v[164:165], off
	v_add3_u32 v155, s13, v150, v149
	v_add_u32_e32 v155, v155, v152
	v_add3_u32 v0, s13, v147, v149
	v_add_u32_e32 v0, v0, v152
	ds_read_b128 v[208:211], v155 offset:32768
	ds_read_b128 v[212:215], v155 offset:36864
	s_waitcnt lgkmcnt(5)
	v_mfma_f32_32x32x16_bf16 v[114:129], v[192:195], v[156:159], v[114:129]
	v_mfma_f32_32x32x16_bf16 v[98:113], v[192:195], v[160:163], v[98:113]
	ds_read_b128 v[192:195], v0
	s_waitcnt lgkmcnt(5)
	v_mfma_f32_32x32x16_bf16 v[82:97], v[196:199], v[156:159], v[82:97]
	v_mfma_f32_32x32x16_bf16 v[66:81], v[196:199], v[160:163], v[66:81]
	ds_read_b128 v[196:199], v0 offset:4096
	s_waitcnt lgkmcnt(5)
	v_mfma_f32_32x32x16_bf16 v[50:65], v[200:203], v[156:159], v[50:65]
	v_mfma_f32_32x32x16_bf16 v[34:49], v[200:203], v[160:163], v[34:49]
	ds_read_b128 v[200:203], v0 offset:8192
	s_waitcnt lgkmcnt(5)
	v_mfma_f32_32x32x16_bf16 v[18:33], v[204:207], v[156:159], v[18:33]
	v_mfma_f32_32x32x16_bf16 v[2:17], v[204:207], v[160:163], v[2:17]
	ds_read_b128 v[204:207], v0 offset:12288
	v_add3_u32 v155, s13, v150, v149
	v_add_u32_e32 v155, v155, v153
	v_add3_u32 v0, s13, v147, v149
	v_add_u32_e32 v0, v0, v153
	ds_read_b128 v[156:159], v155 offset:32768
	ds_read_b128 v[160:163], v155 offset:36864
	s_waitcnt lgkmcnt(5)
	v_mfma_f32_32x32x16_bf16 v[114:129], v[192:195], v[208:211], v[114:129]
	v_mfma_f32_32x32x16_bf16 v[98:113], v[192:195], v[212:215], v[98:113]
	ds_read_b128 v[192:195], v0
	s_waitcnt lgkmcnt(5)
	v_mfma_f32_32x32x16_bf16 v[82:97], v[196:199], v[208:211], v[82:97]
	v_mfma_f32_32x32x16_bf16 v[66:81], v[196:199], v[212:215], v[66:81]
	ds_read_b128 v[196:199], v0 offset:4096
	s_waitcnt lgkmcnt(5)
	v_mfma_f32_32x32x16_bf16 v[50:65], v[200:203], v[208:211], v[50:65]
	v_mfma_f32_32x32x16_bf16 v[34:49], v[200:203], v[212:215], v[34:49]
	ds_read_b128 v[200:203], v0 offset:8192
	s_waitcnt lgkmcnt(5)
	v_mfma_f32_32x32x16_bf16 v[18:33], v[204:207], v[208:211], v[18:33]
	v_mfma_f32_32x32x16_bf16 v[2:17], v[204:207], v[212:215], v[2:17]
	ds_read_b128 v[204:207], v0 offset:12288
	v_add3_u32 v155, s13, v150, v149
	v_add_u32_e32 v155, v155, v154
	v_add3_u32 v0, s13, v147, v149
	v_add_u32_e32 v0, v0, v154
	ds_read_b128 v[208:211], v155 offset:32768
	ds_read_b128 v[212:215], v155 offset:36864
	s_waitcnt lgkmcnt(5)
	v_mfma_f32_32x32x16_bf16 v[114:129], v[192:195], v[156:159], v[114:129]
	v_mfma_f32_32x32x16_bf16 v[98:113], v[192:195], v[160:163], v[98:113]
	ds_read_b128 v[192:195], v0
	s_waitcnt lgkmcnt(5)
	v_mfma_f32_32x32x16_bf16 v[82:97], v[196:199], v[156:159], v[82:97]
	v_mfma_f32_32x32x16_bf16 v[66:81], v[196:199], v[160:163], v[66:81]
	ds_read_b128 v[196:199], v0 offset:4096
	s_waitcnt lgkmcnt(5)
	v_mfma_f32_32x32x16_bf16 v[50:65], v[200:203], v[156:159], v[50:65]
	v_mfma_f32_32x32x16_bf16 v[34:49], v[200:203], v[160:163], v[34:49]
	ds_read_b128 v[200:203], v0 offset:8192
	s_waitcnt lgkmcnt(5)
	v_mfma_f32_32x32x16_bf16 v[18:33], v[204:207], v[156:159], v[18:33]
	v_mfma_f32_32x32x16_bf16 v[2:17], v[204:207], v[160:163], v[2:17]
	ds_read_b128 v[204:207], v0 offset:12288
	s_waitcnt lgkmcnt(3)
	v_mfma_f32_32x32x16_bf16 v[114:129], v[192:195], v[208:211], v[114:129]
	v_mfma_f32_32x32x16_bf16 v[98:113], v[192:195], v[212:215], v[98:113]
	s_waitcnt lgkmcnt(2)
	v_mfma_f32_32x32x16_bf16 v[82:97], v[196:199], v[208:211], v[82:97]
	v_mfma_f32_32x32x16_bf16 v[66:81], v[196:199], v[212:215], v[66:81]
	s_waitcnt lgkmcnt(1)
	v_mfma_f32_32x32x16_bf16 v[50:65], v[200:203], v[208:211], v[50:65]
	v_mfma_f32_32x32x16_bf16 v[34:49], v[200:203], v[212:215], v[34:49]
	s_waitcnt lgkmcnt(0)
	s_waitcnt vmcnt(0)
	s_barrier
; template <int EPI, int AMAP, int KOFFMODE, int K>
; __device__ __forceinline__ void gemm_phase(unsigned char* smem, const bf16_t* A, int lda, const bf16_t* Bt, int NT, const EpiArgs& ea) {
;     ...
;             fb[0][0] = *(const bf16x8*)(Bc + (((0) ^ yz) & 7) * 16);
;             fb[0][1] = *(const bf16x8*)(Bc + 32 * 128 + (((0) ^ yz) & 7) * 16);
; #pragma unroll
;             for (int i = 0; i < 4; ++i) fa[0][i] = *(const bf16x8*)(Ac + i * 32 * 128 + (((0) ^ yz) & 7) * 16);
; #pragma unroll
;             for (int s = 0; s < 4; ++s) {
;                 if (s < 3) {
;                     const int o_ = (((2 * (s + 1)) ^ yz) & 7) * 16;
;                     fb[(s + 1) & 1][0] = *(const bf16x8*)(Bc + o_);
;                     fb[(s + 1) & 1][1] = *(const bf16x8*)(Bc + 32 * 128 + o_);
; #pragma unroll
;                     for (int i = 0; i < 4; ++i) fa[(s + 1) & 1][i] = *(const bf16x8*)(Ac + i * 32 * 128 + o_);
;                 }
; #pragma unroll
;                 for (int i = 0; i < 4; ++i) {
;                     acc[i][0] = __builtin_amdgcn_mfma_f32_32x32x16_bf16(fa[s & 1][i], fb[s & 1][0], acc[i][0], 0, 0, 0);
;                     acc[i][1] = __builtin_amdgcn_mfma_f32_32x32x16_bf16(fa[s & 1][i], fb[s & 1][1], acc[i][1], 0, 0, 0);
;                 }
;                 __builtin_amdgcn_sched_barrier(0);
;             }
;             if (kt + 1 < nk) asm volatile("s_waitcnt vmcnt(0)" ::: "memory");
;             __builtin_amdgcn_s_barrier();
;             cur ^= 1;
;         }
;         gemm_epilogue<EPI>(smem + (cur ^ 1) * STGB, acc, m0, n0, wm, wn, lane, ea);
;         ++rr; u = un; have = have_next; m0 = m0n; n0 = n0n;
	v_add3_u32 v155, s12, v150, v149
	v_add_u32_e32 v155, v155, v151
	v_add3_u32 v0, s12, v147, v149
	v_add_u32_e32 v0, v0, v151
	ds_read_b128 v[156:159], v155 offset:32768
	ds_read_b128 v[160:163], v155 offset:36864
	ds_read_b128 v[192:195], v0
	ds_read_b128 v[196:199], v0 offset:4096
	ds_read_b128 v[200:203], v0 offset:8192
	v_mfma_f32_32x32x16_bf16 v[18:33], v[204:207], v[208:211], v[18:33]
	v_mfma_f32_32x32x16_bf16 v[2:17], v[204:207], v[212:215], v[2:17]
	ds_read_b128 v[204:207], v0 offset:12288
	s_xor_b32 s13, s9, 1
	s_add_u32 s4, s4, 0x80
	s_addc_u32 s5, s5, 0
	s_cmpk_eq_i32 s4, 0xb80
	s_cbranch_scc0 .LBB0_461
	s_waitcnt lgkmcnt(0)
	s_andn2_b64 vcc, exec, s[2:3]
	s_lshl_b32 s2, s13, 16
	s_cbranch_vccnz .LBB0_453
	v_add_u32_e32 v0, s8, v142
	s_xor_b32 s3, s2, 0x10000
	v_mad_i64_i32 v[138:139], s[4:5], v0, s37, v[130:131]
	v_add_u32_e32 v0, s3, v143
	v_add_u32_e32 v136, s7, v142
	v_add_u32_e32 v155, 0x8000, v0
	v_readfirstlane_b32 s3, v0
	v_mad_i64_i32 v[136:137], s[4:5], v136, s37, v[132:133]
	s_mov_b32 m0, s3
	v_readfirstlane_b32 s3, v155
	v_add_u32_e32 v155, 0x2000, v0
	global_load_lds_dwordx4 v[138:139], off
	s_mov_b32 m0, s3
	s_mov_b64 s[4:5], 0x30000
	v_readfirstlane_b32 s3, v155
	v_add_u32_e32 v155, 0xa000, v0
	global_load_lds_dwordx4 v[136:137], off
	v_lshl_add_u64 v[156:157], v[138:139], 0, s[4:5]
	s_mov_b32 m0, s3
	v_readfirstlane_b32 s3, v155
	v_add_u32_e32 v155, 0x4000, v0
	global_load_lds_dwordx4 v[156:157], off
	v_lshl_add_u64 v[156:157], v[136:137], 0, s[4:5]
	s_mov_b32 m0, s3
	s_mov_b64 s[4:5], 0x60000
	v_readfirstlane_b32 s3, v155
	v_add_u32_e32 v155, 0xc000, v0
	global_load_lds_dwordx4 v[156:157], off
	v_lshl_add_u64 v[156:157], v[138:139], 0, s[4:5]
	s_mov_b32 m0, s3
	v_readfirstlane_b32 s3, v155
	v_add_u32_e32 v155, 0x6000, v0
	global_load_lds_dwordx4 v[156:157], off
	v_lshl_add_u64 v[156:157], v[136:137], 0, s[4:5]
	s_mov_b32 m0, s3
	s_mov_b64 s[4:5], 0x90000
	v_readfirstlane_b32 s3, v155
	v_add_u32_e32 v0, 0xe000, v0
	global_load_lds_dwordx4 v[156:157], off
	v_lshl_add_u64 v[138:139], v[138:139], 0, s[4:5]
	s_mov_b32 m0, s3
	v_readfirstlane_b32 s3, v0
	global_load_lds_dwordx4 v[138:139], off
	v_lshl_add_u64 v[136:137], v[136:137], 0, s[4:5]
	s_mov_b32 m0, s3
	s_nop 0
	global_load_lds_dwordx4 v[136:137], off
	s_branch .LBB0_453

; template <int EPI, int AMAP, int KOFFMODE, int K>
; __device__ __forceinline__ void gemm_phase(unsigned char* smem, const bf16_t* A, int lda, const bf16_t* Bt, int NT, const EpiArgs& ea) {
;     ...
;         for (int kt = 0; kt < nk; ++kt) {
;             if (kt + 1 < nk) GEMM_DMA(m0, n0, kt + 1, cur ^ 1);
;             else if (have_next) GEMM_DMA(m0n, n0n, 0, cur ^ 1);
;             const unsigned char* Ac = smem + cur * STGB + (wm * 128 + l31) * 128;
;             const unsigned char* Bc = smem + cur * STGB + 32768 + (wn * 64 + l31) * 128;
;             bf16x8 fa[2][4], fb[2][2];
;             fb[0][0] = *(const bf16x8*)(Bc + (((0) ^ yz) & 7) * 16);
;             fb[0][1] = *(const bf16x8*)(Bc + 32 * 128 + (((0) ^ yz) & 7) * 16);
; #pragma unroll
;             for (int i = 0; i < 4; ++i) fa[0][i] = *(const bf16x8*)(Ac + i * 32 * 128 + (((0) ^ yz) & 7) * 16);
; #pragma unroll
;             for (int s = 0; s < 4; ++s) {
;                 if (s < 3) {
;                     const int o_ = (((2 * (s + 1)) ^ yz) & 7) * 16;
;                     fb[(s + 1) & 1][0] = *(const bf16x8*)(Bc + o_);
;                     fb[(s + 1) & 1][1] = *(const bf16x8*)(Bc + 32 * 128 + o_);
; #pragma unroll
;                     for (int i = 0; i < 4; ++i) fa[(s + 1) & 1][i] = *(const bf16x8*)(Ac + i * 32 * 128 + o_);
;                 }
; #pragma unroll
;                 for (int i = 0; i < 4; ++i) {
;                     acc[i][0] = __builtin_amdgcn_mfma_f32_32x32x16_bf16(fa[s & 1][i], fb[s & 1][0], acc[i][0], 0, 0, 0);
;                     acc[i][1] = __builtin_amdgcn_mfma_f32_32x32x16_bf16(fa[s & 1][i], fb[s & 1][1], acc[i][1], 0, 0, 0);
;                 }
;                 __builtin_amdgcn_sched_barrier(0);
;             }
;             if (kt + 1 < nk) asm volatile("s_waitcnt vmcnt(0)" ::: "memory");
;             __builtin_amdgcn_s_barrier();
.LBB0_927:
	s_lshr_b32 s14, s12, 1
	s_mulk_i32 s14, 0xc0
	s_and_b32 s20, s13, 64
	s_add_i32 s20, s14, s20
	s_mov_b32 s9, s15
	s_lshl_b32 s15, s9, 16
	s_xor_b32 s14, s15, 0x10000
	v_readfirstlane_b32 s28, v143
	s_nop 0
	s_add_u32 s28, s28, s14
	s_lshl_b64 s[34:35], s[20:21], 1
	s_mov_b32 m0, s28
	v_lshl_add_u64 v[164:165], v[136:137], 0, s[34:35]
	global_load_lds_dwordx4 v[164:165], off
	s_lshl_b64 s[34:35], s[20:21], 1
	s_add_u32 s34, s34, 0x60000
	s_addc_u32 s35, s35, 0
	s_add_u32 m0, s28, 0x2000
	v_lshl_add_u64 v[164:165], v[136:137], 0, s[34:35]
	global_load_lds_dwordx4 v[164:165], off
	s_lshl_b64 s[34:35], s[20:21], 1
	s_add_u32 s34, s34, 0xc0000
	s_addc_u32 s35, s35, 0
	s_add_u32 m0, s28, 0x4000
	v_lshl_add_u64 v[164:165], v[136:137], 0, s[34:35]
	global_load_lds_dwordx4 v[164:165], off
	s_lshl_b64 s[34:35], s[20:21], 1
	s_add_u32 s34, s34, 0x120000
	s_addc_u32 s35, s35, 0
	s_add_u32 m0, s28, 0x6000
	v_lshl_add_u64 v[164:165], v[136:137], 0, s[34:35]
	global_load_lds_dwordx4 v[164:165], off
	s_add_u32 s34, s4, 0x7c0080
	s_addc_u32 s35, s5, 0
	s_add_u32 m0, s28, 0x8000
	v_lshl_add_u64 v[164:165], v[138:139], 0, s[34:35]
	global_load_lds_dwordx4 v[164:165], off
	s_add_u32 s34, s4, s68
	s_addc_u32 s35, s5, s69
	s_add_u32 m0, s28, 0xa000
	v_lshl_add_u64 v[164:165], v[138:139], 0, s[34:35]
	global_load_lds_dwordx4 v[164:165], off
	s_add_u32 s34, s4, s80
	s_addc_u32 s35, s5, s81
	s_add_u32 m0, s28, 0xc000
	v_lshl_add_u64 v[164:165], v[138:139], 0, s[34:35]
	global_load_lds_dwordx4 v[164:165], off
	s_add_u32 s34, s4, 0x880080
	s_addc_u32 s35, s5, 0
	s_add_u32 m0, s28, 0xe000
	v_lshl_add_u64 v[164:165], v[138:139], 0, s[34:35]
	global_load_lds_dwordx4 v[164:165], off
	v_add3_u32 v155, s15, v150, v149
	v_add_u32_e32 v155, v155, v152
	v_add3_u32 v0, s15, v147, v149
	v_add_u32_e32 v0, v0, v152
	ds_read_b128 v[208:211], v155 offset:32768
	ds_read_b128 v[212:215], v155 offset:36864
	s_waitcnt lgkmcnt(5)
	v_mfma_f32_32x32x16_bf16 v[114:129], v[192:195], v[156:159], v[114:129]
	v_mfma_f32_32x32x16_bf16 v[98:113], v[192:195], v[160:163], v[98:113]
	ds_read_b128 v[192:195], v0
	s_waitcnt lgkmcnt(5)
	v_mfma_f32_32x32x16_bf16 v[82:97], v[196:199], v[156:159], v[82:97]
	v_mfma_f32_32x32x16_bf16 v[66:81], v[196:199], v[160:163], v[66:81]
	ds_read_b128 v[196:199], v0 offset:4096
	s_waitcnt lgkmcnt(5)
	v_mfma_f32_32x32x16_bf16 v[50:65], v[200:203], v[156:159], v[50:65]
	v_mfma_f32_32x32x16_bf16 v[34:49], v[200:203], v[160:163], v[34:49]
	ds_read_b128 v[200:203], v0 offset:8192
	s_waitcnt lgkmcnt(5)
	v_mfma_f32_32x32x16_bf16 v[18:33], v[204:207], v[156:159], v[18:33]
	v_mfma_f32_32x32x16_bf16 v[2:17], v[204:207], v[160:163], v[2:17]
	ds_read_b128 v[204:207], v0 offset:12288
	v_add3_u32 v155, s15, v150, v149
	v_add_u32_e32 v155, v155, v153
	v_add3_u32 v0, s15, v147, v149
	v_add_u32_e32 v0, v0, v153
	ds_read_b128 v[156:159], v155 offset:32768
	ds_read_b128 v[160:163], v155 offset:36864
	s_waitcnt lgkmcnt(5)
	v_mfma_f32_32x32x16_bf16 v[114:129], v[192:195], v[208:211], v[114:129]
	v_mfma_f32_32x32x16_bf16 v[98:113], v[192:195], v[212:215], v[98:113]
	ds_read_b128 v[192:195], v0
	s_waitcnt lgkmcnt(5)
	v_mfma_f32_32x32x16_bf16 v[82:97], v[196:199], v[208:211], v[82:97]
	v_mfma_f32_32x32x16_bf16 v[66:81], v[196:199], v[212:215], v[66:81]
	ds_read_b128 v[196:199], v0 offset:4096
	s_waitcnt lgkmcnt(5)
	v_mfma_f32_32x32x16_bf16 v[50:65], v[200:203], v[208:211], v[50:65]
	v_mfma_f32_32x32x16_bf16 v[34:49], v[200:203], v[212:215], v[34:49]
	ds_read_b128 v[200:203], v0 offset:8192
	s_waitcnt lgkmcnt(5)
	v_mfma_f32_32x32x16_bf16 v[18:33], v[204:207], v[208:211], v[18:33]
	v_mfma_f32_32x32x16_bf16 v[2:17], v[204:207], v[212:215], v[2:17]
	ds_read_b128 v[204:207], v0 offset:12288
	v_add3_u32 v155, s15, v150, v149
	v_add_u32_e32 v155, v155, v154
	v_add3_u32 v0, s15, v147, v149
	v_add_u32_e32 v0, v0, v154
	ds_read_b128 v[208:211], v155 offset:32768
	ds_read_b128 v[212:215], v155 offset:36864
	s_waitcnt lgkmcnt(5)
	v_mfma_f32_32x32x16_bf16 v[114:129], v[192:195], v[156:159], v[114:129]
	v_mfma_f32_32x32x16_bf16 v[98:113], v[192:195], v[160:163], v[98:113]
	ds_read_b128 v[192:195], v0
	s_waitcnt lgkmcnt(5)
	v_mfma_f32_32x32x16_bf16 v[82:97], v[196:199], v[156:159], v[82:97]
	v_mfma_f32_32x32x16_bf16 v[66:81], v[196:199], v[160:163], v[66:81]
	ds_read_b128 v[196:199], v0 offset:4096
	s_waitcnt lgkmcnt(5)
	v_mfma_f32_32x32x16_bf16 v[50:65], v[200:203], v[156:159], v[50:65]
	v_mfma_f32_32x32x16_bf16 v[34:49], v[200:203], v[160:163], v[34:49]
	ds_read_b128 v[200:203], v0 offset:8192
	s_waitcnt lgkmcnt(5)
	v_mfma_f32_32x32x16_bf16 v[18:33], v[204:207], v[156:159], v[18:33]
	v_mfma_f32_32x32x16_bf16 v[2:17], v[204:207], v[160:163], v[2:17]
	ds_read_b128 v[204:207], v0 offset:12288
	s_waitcnt lgkmcnt(3)
	v_mfma_f32_32x32x16_bf16 v[114:129], v[192:195], v[208:211], v[114:129]
	v_mfma_f32_32x32x16_bf16 v[98:113], v[192:195], v[212:215], v[98:113]
	s_waitcnt lgkmcnt(2)
	v_mfma_f32_32x32x16_bf16 v[82:97], v[196:199], v[208:211], v[82:97]
	v_mfma_f32_32x32x16_bf16 v[66:81], v[196:199], v[212:215], v[66:81]
	s_waitcnt lgkmcnt(1)
	v_mfma_f32_32x32x16_bf16 v[50:65], v[200:203], v[208:211], v[50:65]
	v_mfma_f32_32x32x16_bf16 v[34:49], v[200:203], v[212:215], v[34:49]
	s_waitcnt lgkmcnt(0)
	s_waitcnt vmcnt(0)
	s_barrier
; template <int EPI, int AMAP, int KOFFMODE, int K>
; __device__ __forceinline__ void gemm_phase(unsigned char* smem, const bf16_t* A, int lda, const bf16_t* Bt, int NT, const EpiArgs& ea) {
;     ...
;             fb[0][0] = *(const bf16x8*)(Bc + (((0) ^ yz) & 7) * 16);
;             fb[0][1] = *(const bf16x8*)(Bc + 32 * 128 + (((0) ^ yz) & 7) * 16);
; #pragma unroll
;             for (int i = 0; i < 4; ++i) fa[0][i] = *(const bf16x8*)(Ac + i * 32 * 128 + (((0) ^ yz) & 7) * 16);
; #pragma unroll
;             for (int s = 0; s < 4; ++s) {
;                 if (s < 3) {
;                     const int o_ = (((2 * (s + 1)) ^ yz) & 7) * 16;
;                     fb[(s + 1) & 1][0] = *(const bf16x8*)(Bc + o_);
;                     fb[(s + 1) & 1][1] = *(const bf16x8*)(Bc + 32 * 128 + o_);
; #pragma unroll
;                     for (int i = 0; i < 4; ++i) fa[(s + 1) & 1][i] = *(const bf16x8*)(Ac + i * 32 * 128 + o_);
;                 }
; #pragma unroll
;                 for (int i = 0; i < 4; ++i) {
;                     acc[i][0] = __builtin_amdgcn_mfma_f32_32x32x16_bf16(fa[s & 1][i], fb[s & 1][0], acc[i][0], 0, 0, 0);
;                     acc[i][1] = __builtin_amdgcn_mfma_f32_32x32x16_bf16(fa[s & 1][i], fb[s & 1][1], acc[i][1], 0, 0, 0);
;                 }
;                 __builtin_amdgcn_sched_barrier(0);
;             }
;             if (kt + 1 < nk) asm volatile("s_waitcnt vmcnt(0)" ::: "memory");
;             __builtin_amdgcn_s_barrier();
;             cur ^= 1;
;         }
;         gemm_epilogue<EPI>(smem + (cur ^ 1) * STGB, acc, m0, n0, wm, wn, lane, ea);
;         ++rr; u = un; have = have_next; m0 = m0n; n0 = n0n;
	v_add3_u32 v155, s14, v150, v149
	v_add_u32_e32 v155, v155, v151
	v_add3_u32 v0, s14, v147, v149
	v_add_u32_e32 v0, v0, v151
	ds_read_b128 v[156:159], v155 offset:32768
	ds_read_b128 v[160:163], v155 offset:36864
	ds_read_b128 v[192:195], v0
	ds_read_b128 v[196:199], v0 offset:4096
	ds_read_b128 v[200:203], v0 offset:8192
	v_mfma_f32_32x32x16_bf16 v[18:33], v[204:207], v[208:211], v[18:33]
	v_mfma_f32_32x32x16_bf16 v[2:17], v[204:207], v[212:215], v[2:17]
	ds_read_b128 v[204:207], v0 offset:12288
	s_xor_b32 s15, s9, 1
	s_add_u32 s4, s4, 0x80
	s_addc_u32 s5, s5, 0
	s_add_i32 s12, s12, 1
	s_add_i32 s13, s13, 64
	s_mov_b64 s[34:35], 0x60000
	s_cmpk_eq_i32 s4, 0xf80
	s_cbranch_scc0 .LBB0_927
	s_waitcnt lgkmcnt(0)
	v_writelane_b32 v251, s20, 18
	s_andn2_b64 vcc, exec, s[2:3]
	s_lshl_b32 s2, s15, 16
	v_writelane_b32 v251, s21, 19
	s_cbranch_vccnz .LBB0_919
	v_add_u32_e32 v0, s8, v142
	s_movk_i32 s3, 0x1800
	v_mad_i64_i32 v[138:139], s[4:5], v0, s3, v[130:131]
	s_xor_b32 s3, s2, 0x10000
	v_add_u32_e32 v136, s7, v142
	v_add_u32_e32 v0, s3, v143
	v_ashrrev_i32_e32 v137, 31, v136
	v_add_u32_e32 v155, 0x8000, v0
	v_readfirstlane_b32 s3, v0
	v_lshlrev_b64 v[136:137], 12, v[136:137]
	s_mov_b32 m0, s3
	v_readfirstlane_b32 s3, v155
	v_add_u32_e32 v155, 0x2000, v0
	v_lshl_add_u64 v[136:137], v[132:133], 0, v[136:137]
	global_load_lds_dwordx4 v[138:139], off
	s_mov_b32 m0, s3
	v_readfirstlane_b32 s3, v155
	v_add_u32_e32 v155, 0xa000, v0
	global_load_lds_dwordx4 v[136:137], off
	v_lshl_add_u64 v[156:157], v[138:139], 0, s[34:35]
	s_mov_b32 m0, s3
	s_mov_b64 s[4:5], 0x40000
	v_readfirstlane_b32 s3, v155
	v_add_u32_e32 v155, 0x4000, v0
	global_load_lds_dwordx4 v[156:157], off
	v_lshl_add_u64 v[156:157], v[136:137], 0, s[4:5]
	s_mov_b32 m0, s3
	s_mov_b64 s[4:5], 0xc0000
	v_readfirstlane_b32 s3, v155
	v_add_u32_e32 v155, 0xc000, v0
	global_load_lds_dwordx4 v[156:157], off
	v_lshl_add_u64 v[156:157], v[138:139], 0, s[4:5]
	s_mov_b32 m0, s3
	s_mov_b64 s[12:13], 0x80000
	v_readfirstlane_b32 s3, v155
	v_add_u32_e32 v155, 0x6000, v0
	global_load_lds_dwordx4 v[156:157], off
	v_lshl_add_u64 v[156:157], v[136:137], 0, s[12:13]
	s_mov_b32 m0, s3
	s_mov_b64 s[12:13], 0x120000
	v_readfirstlane_b32 s3, v155
	v_add_u32_e32 v0, 0xe000, v0
	global_load_lds_dwordx4 v[156:157], off
	v_lshl_add_u64 v[138:139], v[138:139], 0, s[12:13]
	s_mov_b32 m0, s3
	v_readfirstlane_b32 s3, v0
	global_load_lds_dwordx4 v[138:139], off
	v_lshl_add_u64 v[136:137], v[136:137], 0, s[4:5]
	s_mov_b32 m0, s3
	s_nop 0
	global_load_lds_dwordx4 v[136:137], off
	s_branch .LBB0_919

; template <int EPI, int AMAP, int KOFFMODE, int K>
; __device__ __forceinline__ void gemm_phase(unsigned char* smem, const bf16_t* A, int lda, const bf16_t* Bt, int NT, const EpiArgs& ea) {
;     ...
;         for (int kt = 0; kt < nk; ++kt) {
;             if (kt + 1 < nk) GEMM_DMA(m0, n0, kt + 1, cur ^ 1);
;             else if (have_next) GEMM_DMA(m0n, n0n, 0, cur ^ 1);
;             const unsigned char* Ac = smem + cur * STGB + (wm * 128 + l31) * 128;
;             const unsigned char* Bc = smem + cur * STGB + 32768 + (wn * 64 + l31) * 128;
;             bf16x8 fa[2][4], fb[2][2];
;             fb[0][0] = *(const bf16x8*)(Bc + (((0) ^ yz) & 7) * 16);
;             fb[0][1] = *(const bf16x8*)(Bc + 32 * 128 + (((0) ^ yz) & 7) * 16);
; #pragma unroll
;             for (int i = 0; i < 4; ++i) fa[0][i] = *(const bf16x8*)(Ac + i * 32 * 128 + (((0) ^ yz) & 7) * 16);
; #pragma unroll
;             for (int s = 0; s < 4; ++s) {
;                 if (s < 3) {
;                     const int o_ = (((2 * (s + 1)) ^ yz) & 7) * 16;
;                     fb[(s + 1) & 1][0] = *(const bf16x8*)(Bc + o_);
;                     fb[(s + 1) & 1][1] = *(const bf16x8*)(Bc + 32 * 128 + o_);
; #pragma unroll
;                     for (int i = 0; i < 4; ++i) fa[(s + 1) & 1][i] = *(const bf16x8*)(Ac + i * 32 * 128 + o_);
;                 }
; #pragma unroll
;                 for (int i = 0; i < 4; ++i) {
;                     acc[i][0] = __builtin_amdgcn_mfma_f32_32x32x16_bf16(fa[s & 1][i], fb[s & 1][0], acc[i][0], 0, 0, 0);
;                     acc[i][1] = __builtin_amdgcn_mfma_f32_32x32x16_bf16(fa[s & 1][i], fb[s & 1][1], acc[i][1], 0, 0, 0);
;                 }
;                 __builtin_amdgcn_sched_barrier(0);
;             }
;             if (kt + 1 < nk) asm volatile("s_waitcnt vmcnt(0)" ::: "memory");
;             __builtin_amdgcn_s_barrier();
.LBB0_1032:
	s_mov_b32 s11, s15
	s_lshl_b32 s15, s11, 16
	s_xor_b32 s14, s15, 0x10000
	v_readfirstlane_b32 s28, v144
	s_nop 0
	s_add_u32 s28, s28, s14
	s_add_u32 s34, s4, s20
	s_addc_u32 s35, s5, s21
	s_mov_b32 m0, s28
	v_lshl_add_u64 v[164:165], v[136:137], 0, s[34:35]
	global_load_lds_dwordx4 v[164:165], off
	s_add_u32 s34, s4, vcc_lo
	s_addc_u32 s35, s5, vcc_hi
	s_add_u32 m0, s28, 0x2000
	v_lshl_add_u64 v[164:165], v[136:137], 0, s[34:35]
	global_load_lds_dwordx4 v[164:165], off
	s_add_u32 s34, s4, s68
	s_addc_u32 s35, s5, s69
	s_add_u32 m0, s28, 0x4000
	v_lshl_add_u64 v[164:165], v[136:137], 0, s[34:35]
	global_load_lds_dwordx4 v[164:165], off
	s_add_u32 s34, s4, s88
	s_addc_u32 s35, s5, s89
	s_add_u32 m0, s28, 0x6000
	v_lshl_add_u64 v[164:165], v[136:137], 0, s[34:35]
	global_load_lds_dwordx4 v[164:165], off
	s_add_u32 s34, s4, 0xe00080
	s_addc_u32 s35, s5, 0
	s_add_u32 m0, s28, 0x8000
	v_lshl_add_u64 v[164:165], v[138:139], 0, s[34:35]
	global_load_lds_dwordx4 v[164:165], off
	s_add_u32 s34, s4, 0xe20080
	s_addc_u32 s35, s5, 0
	s_add_u32 m0, s28, 0xa000
	v_lshl_add_u64 v[164:165], v[138:139], 0, s[34:35]
	global_load_lds_dwordx4 v[164:165], off
	s_add_u32 s34, s4, 0xe40080
	s_addc_u32 s35, s5, 0
	s_add_u32 m0, s28, 0xc000
	v_lshl_add_u64 v[164:165], v[138:139], 0, s[34:35]
	global_load_lds_dwordx4 v[164:165], off
	s_add_u32 s34, s4, 0xe60080
	s_addc_u32 s35, s5, 0
	s_add_u32 m0, s28, 0xe000
	v_lshl_add_u64 v[164:165], v[138:139], 0, s[34:35]
	global_load_lds_dwordx4 v[164:165], off
	v_add3_u32 v191, s15, v151, v150
	v_add_u32_e32 v191, v191, v153
	v_add3_u32 v0, s15, v149, v150
	v_add_u32_e32 v0, v0, v153
	ds_read_b128 v[208:211], v191 offset:32768
	ds_read_b128 v[212:215], v191 offset:36864
	s_waitcnt lgkmcnt(5)
	v_mfma_f32_32x32x16_bf16 v[114:129], v[192:195], v[156:159], v[114:129]
	v_mfma_f32_32x32x16_bf16 v[98:113], v[192:195], v[160:163], v[98:113]
	ds_read_b128 v[192:195], v0
	s_waitcnt lgkmcnt(5)
	v_mfma_f32_32x32x16_bf16 v[82:97], v[196:199], v[156:159], v[82:97]
	v_mfma_f32_32x32x16_bf16 v[66:81], v[196:199], v[160:163], v[66:81]
	ds_read_b128 v[196:199], v0 offset:4096
	s_waitcnt lgkmcnt(5)
	v_mfma_f32_32x32x16_bf16 v[50:65], v[200:203], v[156:159], v[50:65]
	v_mfma_f32_32x32x16_bf16 v[34:49], v[200:203], v[160:163], v[34:49]
	ds_read_b128 v[200:203], v0 offset:8192
	s_waitcnt lgkmcnt(5)
	v_mfma_f32_32x32x16_bf16 v[18:33], v[204:207], v[156:159], v[18:33]
	v_mfma_f32_32x32x16_bf16 v[2:17], v[204:207], v[160:163], v[2:17]
	ds_read_b128 v[204:207], v0 offset:12288
	v_add3_u32 v191, s15, v151, v150
	v_add_u32_e32 v191, v191, v154
	v_add3_u32 v0, s15, v149, v150
	v_add_u32_e32 v0, v0, v154
	ds_read_b128 v[156:159], v191 offset:32768
	ds_read_b128 v[160:163], v191 offset:36864
	s_waitcnt lgkmcnt(5)
	v_mfma_f32_32x32x16_bf16 v[114:129], v[192:195], v[208:211], v[114:129]
	v_mfma_f32_32x32x16_bf16 v[98:113], v[192:195], v[212:215], v[98:113]
	ds_read_b128 v[192:195], v0
	s_waitcnt lgkmcnt(5)
	v_mfma_f32_32x32x16_bf16 v[82:97], v[196:199], v[208:211], v[82:97]
	v_mfma_f32_32x32x16_bf16 v[66:81], v[196:199], v[212:215], v[66:81]
	ds_read_b128 v[196:199], v0 offset:4096
	s_waitcnt lgkmcnt(5)
	v_mfma_f32_32x32x16_bf16 v[50:65], v[200:203], v[208:211], v[50:65]
	v_mfma_f32_32x32x16_bf16 v[34:49], v[200:203], v[212:215], v[34:49]
	ds_read_b128 v[200:203], v0 offset:8192
	s_waitcnt lgkmcnt(5)
	v_mfma_f32_32x32x16_bf16 v[18:33], v[204:207], v[208:211], v[18:33]
	v_mfma_f32_32x32x16_bf16 v[2:17], v[204:207], v[212:215], v[2:17]
	ds_read_b128 v[204:207], v0 offset:12288
	v_add3_u32 v191, s15, v151, v150
	v_add_u32_e32 v191, v191, v155
	v_add3_u32 v0, s15, v149, v150
	v_add_u32_e32 v0, v0, v155
	ds_read_b128 v[208:211], v191 offset:32768
	ds_read_b128 v[212:215], v191 offset:36864
	s_waitcnt lgkmcnt(5)
	v_mfma_f32_32x32x16_bf16 v[114:129], v[192:195], v[156:159], v[114:129]
	v_mfma_f32_32x32x16_bf16 v[98:113], v[192:195], v[160:163], v[98:113]
	ds_read_b128 v[192:195], v0
	s_waitcnt lgkmcnt(5)
	v_mfma_f32_32x32x16_bf16 v[82:97], v[196:199], v[156:159], v[82:97]
	v_mfma_f32_32x32x16_bf16 v[66:81], v[196:199], v[160:163], v[66:81]
	ds_read_b128 v[196:199], v0 offset:4096
	s_waitcnt lgkmcnt(5)
	v_mfma_f32_32x32x16_bf16 v[50:65], v[200:203], v[156:159], v[50:65]
	v_mfma_f32_32x32x16_bf16 v[34:49], v[200:203], v[160:163], v[34:49]
	ds_read_b128 v[200:203], v0 offset:8192
	s_waitcnt lgkmcnt(5)
	v_mfma_f32_32x32x16_bf16 v[18:33], v[204:207], v[156:159], v[18:33]
	v_mfma_f32_32x32x16_bf16 v[2:17], v[204:207], v[160:163], v[2:17]
	ds_read_b128 v[204:207], v0 offset:12288
	s_waitcnt lgkmcnt(3)
	v_mfma_f32_32x32x16_bf16 v[114:129], v[192:195], v[208:211], v[114:129]
	v_mfma_f32_32x32x16_bf16 v[98:113], v[192:195], v[212:215], v[98:113]
	s_waitcnt lgkmcnt(2)
	v_mfma_f32_32x32x16_bf16 v[82:97], v[196:199], v[208:211], v[82:97]
	v_mfma_f32_32x32x16_bf16 v[66:81], v[196:199], v[212:215], v[66:81]
	s_waitcnt lgkmcnt(1)
	v_mfma_f32_32x32x16_bf16 v[50:65], v[200:203], v[208:211], v[50:65]
	v_mfma_f32_32x32x16_bf16 v[34:49], v[200:203], v[212:215], v[34:49]
	s_waitcnt lgkmcnt(0)
	s_waitcnt vmcnt(0)
	s_barrier
; template <int EPI, int AMAP, int KOFFMODE, int K>
; __device__ __forceinline__ void gemm_phase(unsigned char* smem, const bf16_t* A, int lda, const bf16_t* Bt, int NT, const EpiArgs& ea) {
;     ...
;             fb[0][0] = *(const bf16x8*)(Bc + (((0) ^ yz) & 7) * 16);
;             fb[0][1] = *(const bf16x8*)(Bc + 32 * 128 + (((0) ^ yz) & 7) * 16);
; #pragma unroll
;             for (int i = 0; i < 4; ++i) fa[0][i] = *(const bf16x8*)(Ac + i * 32 * 128 + (((0) ^ yz) & 7) * 16);
; #pragma unroll
;             for (int s = 0; s < 4; ++s) {
;                 if (s < 3) {
;                     const int o_ = (((2 * (s + 1)) ^ yz) & 7) * 16;
;                     fb[(s + 1) & 1][0] = *(const bf16x8*)(Bc + o_);
;                     fb[(s + 1) & 1][1] = *(const bf16x8*)(Bc + 32 * 128 + o_);
; #pragma unroll
;                     for (int i = 0; i < 4; ++i) fa[(s + 1) & 1][i] = *(const bf16x8*)(Ac + i * 32 * 128 + o_);
;                 }
; #pragma unroll
;                 for (int i = 0; i < 4; ++i) {
;                     acc[i][0] = __builtin_amdgcn_mfma_f32_32x32x16_bf16(fa[s & 1][i], fb[s & 1][0], acc[i][0], 0, 0, 0);
;                     acc[i][1] = __builtin_amdgcn_mfma_f32_32x32x16_bf16(fa[s & 1][i], fb[s & 1][1], acc[i][1], 0, 0, 0);
;                 }
;                 __builtin_amdgcn_sched_barrier(0);
;             }
;             if (kt + 1 < nk) asm volatile("s_waitcnt vmcnt(0)" ::: "memory");
;             __builtin_amdgcn_s_barrier();
;             cur ^= 1;
;         }
;         gemm_epilogue<EPI>(smem + (cur ^ 1) * STGB, acc, m0, n0, wm, wn, lane, ea);
;         ++rr; u = un; have = have_next; m0 = m0n; n0 = n0n;
	v_add3_u32 v191, s14, v151, v150
	v_add_u32_e32 v191, v191, v152
	v_add3_u32 v0, s14, v149, v150
	v_add_u32_e32 v0, v0, v152
	ds_read_b128 v[156:159], v191 offset:32768
	ds_read_b128 v[160:163], v191 offset:36864
	ds_read_b128 v[192:195], v0
	ds_read_b128 v[196:199], v0 offset:4096
	ds_read_b128 v[200:203], v0 offset:8192
	v_mfma_f32_32x32x16_bf16 v[18:33], v[204:207], v[208:211], v[18:33]
	v_mfma_f32_32x32x16_bf16 v[2:17], v[204:207], v[212:215], v[2:17]
	ds_read_b128 v[204:207], v0 offset:12288
	s_xor_b32 s15, s11, 1
	s_add_u32 s4, s4, 0x80
	s_addc_u32 s5, s5, 0
	s_cmpk_eq_i32 s4, 0x780
	s_cbranch_scc0 .LBB0_1032
	s_waitcnt lgkmcnt(0)
	s_andn2_b64 vcc, exec, s[2:3]
	s_lshl_b32 s2, s15, 16
	s_cbranch_vccnz .LBB0_1024
	v_add_u32_e32 v136, s10, v143
	s_xor_b32 s3, s2, 0x10000
	v_ashrrev_i32_e32 v137, 31, v136
	v_add_u32_e32 v138, s9, v143
	v_add_u32_e32 v0, s3, v144
	v_lshlrev_b64 v[136:137], 11, v[136:137]
	v_ashrrev_i32_e32 v139, 31, v138
	v_add_u32_e32 v156, 0x8000, v0
	v_readfirstlane_b32 s3, v0
	v_lshlrev_b64 v[138:139], 11, v[138:139]
	v_lshl_add_u64 v[136:137], v[130:131], 0, v[136:137]
	s_mov_b32 m0, s3
	v_readfirstlane_b32 s3, v156
	v_add_u32_e32 v158, 0x2000, v0
	v_lshl_add_u64 v[138:139], v[132:133], 0, v[138:139]
	global_load_lds_dwordx4 v[136:137], off
	s_mov_b32 m0, s3
	s_mov_b64 s[4:5], 0x20000
	v_readfirstlane_b32 s3, v158
	v_add_u32_e32 v158, 0xa000, v0
	global_load_lds_dwordx4 v[138:139], off
	v_lshl_add_u64 v[156:157], v[136:137], 0, s[4:5]
	s_mov_b32 m0, s3
	v_readfirstlane_b32 s3, v158
	v_add_u32_e32 v158, 0x4000, v0
	global_load_lds_dwordx4 v[156:157], off
	v_lshl_add_u64 v[156:157], v[138:139], 0, s[4:5]
	s_mov_b32 m0, s3
	s_mov_b64 s[4:5], 0x40000
	v_readfirstlane_b32 s3, v158
	v_add_u32_e32 v158, 0xc000, v0
	global_load_lds_dwordx4 v[156:157], off
	v_lshl_add_u64 v[156:157], v[136:137], 0, s[4:5]
	s_mov_b32 m0, s3
	v_readfirstlane_b32 s3, v158
	global_load_lds_dwordx4 v[156:157], off
	v_lshl_add_u64 v[156:157], v[138:139], 0, s[4:5]
	s_mov_b32 m0, s3
	s_mov_b64 s[4:5], 0x60000
	global_load_lds_dwordx4 v[156:157], off
	v_add_u32_e32 v156, 0x6000, v0
	v_add_u32_e32 v0, 0xe000, v0
	v_readfirstlane_b32 s3, v156
	v_lshl_add_u64 v[136:137], v[136:137], 0, s[4:5]
	s_mov_b32 m0, s3
	v_readfirstlane_b32 s3, v0
	global_load_lds_dwordx4 v[136:137], off
	v_lshl_add_u64 v[136:137], v[138:139], 0, s[4:5]
	s_mov_b32 m0, s3
	s_nop 0
	global_load_lds_dwordx4 v[136:137], off
	s_branch .LBB0_1024

; template <int EPI, int AMAP, int KOFFMODE, int K>
; __device__ __forceinline__ void gemm_phase(unsigned char* smem, const bf16_t* A, int lda, const bf16_t* Bt, int NT, const EpiArgs& ea) {
;     ...
;         for (int kt = 0; kt < nk; ++kt) {
;             if (kt + 1 < nk) GEMM_DMA(m0, n0, kt + 1, cur ^ 1);
;             else if (have_next) GEMM_DMA(m0n, n0n, 0, cur ^ 1);
;             const unsigned char* Ac = smem + cur * STGB + (wm * 128 + l31) * 128;
;             const unsigned char* Bc = smem + cur * STGB + 32768 + (wn * 64 + l31) * 128;
;             bf16x8 fa[2][4], fb[2][2];
;             fb[0][0] = *(const bf16x8*)(Bc + (((0) ^ yz) & 7) * 16);
;             fb[0][1] = *(const bf16x8*)(Bc + 32 * 128 + (((0) ^ yz) & 7) * 16);
; #pragma unroll
;             for (int i = 0; i < 4; ++i) fa[0][i] = *(const bf16x8*)(Ac + i * 32 * 128 + (((0) ^ yz) & 7) * 16);
; #pragma unroll
;             for (int s = 0; s < 4; ++s) {
;                 if (s < 3) {
;                     const int o_ = (((2 * (s + 1)) ^ yz) & 7) * 16;
;                     fb[(s + 1) & 1][0] = *(const bf16x8*)(Bc + o_);
;                     fb[(s + 1) & 1][1] = *(const bf16x8*)(Bc + 32 * 128 + o_);
; #pragma unroll
;                     for (int i = 0; i < 4; ++i) fa[(s + 1) & 1][i] = *(const bf16x8*)(Ac + i * 32 * 128 + o_);
;                 }
; #pragma unroll
;                 for (int i = 0; i < 4; ++i) {
;                     acc[i][0] = __builtin_amdgcn_mfma_f32_32x32x16_bf16(fa[s & 1][i], fb[s & 1][0], acc[i][0], 0, 0, 0);
;                     acc[i][1] = __builtin_amdgcn_mfma_f32_32x32x16_bf16(fa[s & 1][i], fb[s & 1][1], acc[i][1], 0, 0, 0);
;                 }
;                 __builtin_amdgcn_sched_barrier(0);
;             }
;             if (kt + 1 < nk) asm volatile("s_waitcnt vmcnt(0)" ::: "memory");
;             __builtin_amdgcn_s_barrier();
.LBB0_1161:
	s_mov_b32 s13, s34
	s_lshl_b32 s36, s13, 16
	s_xor_b32 s28, s36, 0x10000
	v_readfirstlane_b32 vcc_lo, v144
	s_nop 0
	s_add_u32 vcc_lo, vcc_lo, s28
	s_add_u32 s34, s8, 0x4100080
	s_addc_u32 s35, s9, 0
	s_mov_b32 m0, vcc_lo
	v_lshl_add_u64 v[164:165], v[136:137], 0, s[34:35]
	global_load_lds_dwordx4 v[164:165], off
	s_add_u32 s34, s8, 0x4158080
	s_addc_u32 s35, s9, 0
	s_add_u32 m0, vcc_lo, 0x2000
	v_lshl_add_u64 v[164:165], v[136:137], 0, s[34:35]
	global_load_lds_dwordx4 v[164:165], off
	s_add_u32 s34, s8, 0x41b0080
	s_addc_u32 s35, s9, 0
	s_add_u32 m0, vcc_lo, 0x4000
	v_lshl_add_u64 v[164:165], v[136:137], 0, s[34:35]
	global_load_lds_dwordx4 v[164:165], off
	s_add_u32 s34, s8, 0x4208080
	s_addc_u32 s35, s9, 0
	s_add_u32 m0, vcc_lo, 0x6000
	v_lshl_add_u64 v[164:165], v[136:137], 0, s[34:35]
	global_load_lds_dwordx4 v[164:165], off
	s_add_u32 s34, s8, 0x1900080
	s_addc_u32 s35, s9, 0
	s_add_u32 m0, vcc_lo, 0x8000
	v_lshl_add_u64 v[164:165], v[138:139], 0, s[34:35]
	global_load_lds_dwordx4 v[164:165], off
	s_add_u32 s34, s8, 0x1958080
	s_addc_u32 s35, s9, 0
	s_add_u32 m0, vcc_lo, 0xa000
	v_lshl_add_u64 v[164:165], v[138:139], 0, s[34:35]
	global_load_lds_dwordx4 v[164:165], off
	s_add_u32 s34, s8, 0x19b0080
	s_addc_u32 s35, s9, 0
	s_add_u32 m0, vcc_lo, 0xc000
	v_lshl_add_u64 v[164:165], v[138:139], 0, s[34:35]
	global_load_lds_dwordx4 v[164:165], off
	s_add_u32 s34, s8, 0x1a08080
	s_addc_u32 s35, s9, 0
	s_add_u32 m0, vcc_lo, 0xe000
	v_lshl_add_u64 v[164:165], v[138:139], 0, s[34:35]
	global_load_lds_dwordx4 v[164:165], off
	v_add3_u32 v191, s36, v151, v150
	v_add_u32_e32 v191, v191, v153
	v_add3_u32 v0, s36, v149, v150
	v_add_u32_e32 v0, v0, v153
	ds_read_b128 v[208:211], v191 offset:32768
	ds_read_b128 v[212:215], v191 offset:36864
	s_waitcnt lgkmcnt(5)
	v_mfma_f32_32x32x16_bf16 v[114:129], v[192:195], v[156:159], v[114:129]
	v_mfma_f32_32x32x16_bf16 v[98:113], v[192:195], v[160:163], v[98:113]
	ds_read_b128 v[192:195], v0
	s_waitcnt lgkmcnt(5)
	v_mfma_f32_32x32x16_bf16 v[82:97], v[196:199], v[156:159], v[82:97]
	v_mfma_f32_32x32x16_bf16 v[66:81], v[196:199], v[160:163], v[66:81]
	ds_read_b128 v[196:199], v0 offset:4096
	s_waitcnt lgkmcnt(5)
	v_mfma_f32_32x32x16_bf16 v[50:65], v[200:203], v[156:159], v[50:65]
	v_mfma_f32_32x32x16_bf16 v[34:49], v[200:203], v[160:163], v[34:49]
	ds_read_b128 v[200:203], v0 offset:8192
	s_waitcnt lgkmcnt(5)
	v_mfma_f32_32x32x16_bf16 v[18:33], v[204:207], v[156:159], v[18:33]
	v_mfma_f32_32x32x16_bf16 v[2:17], v[204:207], v[160:163], v[2:17]
	ds_read_b128 v[204:207], v0 offset:12288
	v_add3_u32 v191, s36, v151, v150
	v_add_u32_e32 v191, v191, v154
	v_add3_u32 v0, s36, v149, v150
	v_add_u32_e32 v0, v0, v154
	ds_read_b128 v[156:159], v191 offset:32768
	ds_read_b128 v[160:163], v191 offset:36864
	s_waitcnt lgkmcnt(5)
	v_mfma_f32_32x32x16_bf16 v[114:129], v[192:195], v[208:211], v[114:129]
	v_mfma_f32_32x32x16_bf16 v[98:113], v[192:195], v[212:215], v[98:113]
	ds_read_b128 v[192:195], v0
	s_waitcnt lgkmcnt(5)
	v_mfma_f32_32x32x16_bf16 v[82:97], v[196:199], v[208:211], v[82:97]
	v_mfma_f32_32x32x16_bf16 v[66:81], v[196:199], v[212:215], v[66:81]
	ds_read_b128 v[196:199], v0 offset:4096
	s_waitcnt lgkmcnt(5)
	v_mfma_f32_32x32x16_bf16 v[50:65], v[200:203], v[208:211], v[50:65]
	v_mfma_f32_32x32x16_bf16 v[34:49], v[200:203], v[212:215], v[34:49]
	ds_read_b128 v[200:203], v0 offset:8192
	s_waitcnt lgkmcnt(5)
	v_mfma_f32_32x32x16_bf16 v[18:33], v[204:207], v[208:211], v[18:33]
	v_mfma_f32_32x32x16_bf16 v[2:17], v[204:207], v[212:215], v[2:17]
	ds_read_b128 v[204:207], v0 offset:12288
	v_add3_u32 v191, s36, v151, v150
	v_add_u32_e32 v191, v191, v155
	v_add3_u32 v0, s36, v149, v150
	v_add_u32_e32 v0, v0, v155
	ds_read_b128 v[208:211], v191 offset:32768
	ds_read_b128 v[212:215], v191 offset:36864
	s_waitcnt lgkmcnt(5)
	v_mfma_f32_32x32x16_bf16 v[114:129], v[192:195], v[156:159], v[114:129]
	v_mfma_f32_32x32x16_bf16 v[98:113], v[192:195], v[160:163], v[98:113]
	ds_read_b128 v[192:195], v0
	s_waitcnt lgkmcnt(5)
	v_mfma_f32_32x32x16_bf16 v[82:97], v[196:199], v[156:159], v[82:97]
	v_mfma_f32_32x32x16_bf16 v[66:81], v[196:199], v[160:163], v[66:81]
	ds_read_b128 v[196:199], v0 offset:4096
	s_waitcnt lgkmcnt(5)
	v_mfma_f32_32x32x16_bf16 v[50:65], v[200:203], v[156:159], v[50:65]
	v_mfma_f32_32x32x16_bf16 v[34:49], v[200:203], v[160:163], v[34:49]
	ds_read_b128 v[200:203], v0 offset:8192
	s_waitcnt lgkmcnt(5)
	v_mfma_f32_32x32x16_bf16 v[18:33], v[204:207], v[156:159], v[18:33]
	v_mfma_f32_32x32x16_bf16 v[2:17], v[204:207], v[160:163], v[2:17]
	ds_read_b128 v[204:207], v0 offset:12288
	s_waitcnt lgkmcnt(3)
	v_mfma_f32_32x32x16_bf16 v[114:129], v[192:195], v[208:211], v[114:129]
	v_mfma_f32_32x32x16_bf16 v[98:113], v[192:195], v[212:215], v[98:113]
	s_waitcnt lgkmcnt(2)
	v_mfma_f32_32x32x16_bf16 v[82:97], v[196:199], v[208:211], v[82:97]
	v_mfma_f32_32x32x16_bf16 v[66:81], v[196:199], v[212:215], v[66:81]
	s_waitcnt lgkmcnt(1)
	v_mfma_f32_32x32x16_bf16 v[50:65], v[200:203], v[208:211], v[50:65]
	v_mfma_f32_32x32x16_bf16 v[34:49], v[200:203], v[212:215], v[34:49]
	s_waitcnt lgkmcnt(0)
	s_waitcnt vmcnt(0)
	s_barrier
; template <int EPI, int AMAP, int KOFFMODE, int K>
; __device__ __forceinline__ void gemm_phase(unsigned char* smem, const bf16_t* A, int lda, const bf16_t* Bt, int NT, const EpiArgs& ea) {
;     ...
;             fb[0][0] = *(const bf16x8*)(Bc + (((0) ^ yz) & 7) * 16);
;             fb[0][1] = *(const bf16x8*)(Bc + 32 * 128 + (((0) ^ yz) & 7) * 16);
; #pragma unroll
;             for (int i = 0; i < 4; ++i) fa[0][i] = *(const bf16x8*)(Ac + i * 32 * 128 + (((0) ^ yz) & 7) * 16);
; #pragma unroll
;             for (int s = 0; s < 4; ++s) {
;                 if (s < 3) {
;                     const int o_ = (((2 * (s + 1)) ^ yz) & 7) * 16;
;                     fb[(s + 1) & 1][0] = *(const bf16x8*)(Bc + o_);
;                     fb[(s + 1) & 1][1] = *(const bf16x8*)(Bc + 32 * 128 + o_);
; #pragma unroll
;                     for (int i = 0; i < 4; ++i) fa[(s + 1) & 1][i] = *(const bf16x8*)(Ac + i * 32 * 128 + o_);
;                 }
; #pragma unroll
;                 for (int i = 0; i < 4; ++i) {
;                     acc[i][0] = __builtin_amdgcn_mfma_f32_32x32x16_bf16(fa[s & 1][i], fb[s & 1][0], acc[i][0], 0, 0, 0);
;                     acc[i][1] = __builtin_amdgcn_mfma_f32_32x32x16_bf16(fa[s & 1][i], fb[s & 1][1], acc[i][1], 0, 0, 0);
;                 }
;                 __builtin_amdgcn_sched_barrier(0);
;             }
;             if (kt + 1 < nk) asm volatile("s_waitcnt vmcnt(0)" ::: "memory");
;             __builtin_amdgcn_s_barrier();
;             cur ^= 1;
;         }
;         gemm_epilogue<EPI>(smem + (cur ^ 1) * STGB, acc, m0, n0, wm, wn, lane, ea);
;         ++rr; u = un; have = have_next; m0 = m0n; n0 = n0n;
	v_add3_u32 v191, s28, v151, v150
	v_add_u32_e32 v191, v191, v152
	v_add3_u32 v0, s28, v149, v150
	v_add_u32_e32 v0, v0, v152
	ds_read_b128 v[156:159], v191 offset:32768
	ds_read_b128 v[160:163], v191 offset:36864
	ds_read_b128 v[192:195], v0
	ds_read_b128 v[196:199], v0 offset:4096
	ds_read_b128 v[200:203], v0 offset:8192
	v_mfma_f32_32x32x16_bf16 v[18:33], v[204:207], v[208:211], v[18:33]
	v_mfma_f32_32x32x16_bf16 v[2:17], v[204:207], v[212:215], v[2:17]
	ds_read_b128 v[204:207], v0 offset:12288
	s_xor_b32 s34, s13, 1
	s_add_u32 s8, s8, 0x80
	s_addc_u32 s9, s9, 0
	s_cmpk_eq_i32 s8, 0x1580
	s_cbranch_scc0 .LBB0_1161
	s_waitcnt lgkmcnt(0)
	s_andn2_b64 vcc, exec, s[2:3]
	s_lshl_b32 s2, s34, 16
	s_cbranch_vccnz .LBB0_1153
	v_add_u32_e32 v0, s12, v143
	v_add_u32_e32 v136, s11, v143
	s_movk_i32 s3, 0x1600
	v_mad_i64_i32 v[136:137], s[8:9], v136, s3, v[132:133]
	v_mad_i64_i32 v[138:139], s[8:9], v0, s3, v[130:131]
	s_xor_b32 s3, s2, 0x10000
	v_add_u32_e32 v0, s3, v144
	v_add_u32_e32 v156, 0x8000, v0
	v_readfirstlane_b32 s3, v0
	s_mov_b32 m0, s3
	v_readfirstlane_b32 s3, v156
	v_add_u32_e32 v158, 0x2000, v0
	global_load_lds_dwordx4 v[138:139], off
	s_mov_b32 m0, s3
	s_mov_b64 s[8:9], 0x58000
	v_readfirstlane_b32 s3, v158
	v_add_u32_e32 v158, 0xa000, v0
	global_load_lds_dwordx4 v[136:137], off
	v_lshl_add_u64 v[156:157], v[138:139], 0, s[8:9]
	s_mov_b32 m0, s3
	v_readfirstlane_b32 s3, v158
	v_add_u32_e32 v158, 0x4000, v0
	global_load_lds_dwordx4 v[156:157], off
	v_lshl_add_u64 v[156:157], v[136:137], 0, s[8:9]
	s_mov_b32 m0, s3
	s_mov_b64 s[8:9], 0xb0000
	v_readfirstlane_b32 s3, v158
	v_add_u32_e32 v158, 0xc000, v0
	global_load_lds_dwordx4 v[156:157], off
	v_lshl_add_u64 v[156:157], v[138:139], 0, s[8:9]
	s_mov_b32 m0, s3
	v_readfirstlane_b32 s3, v158
	global_load_lds_dwordx4 v[156:157], off
	v_lshl_add_u64 v[156:157], v[136:137], 0, s[8:9]
	s_mov_b32 m0, s3
	s_mov_b64 s[8:9], 0x108000
	global_load_lds_dwordx4 v[156:157], off
	v_add_u32_e32 v156, 0x6000, v0
	v_add_u32_e32 v0, 0xe000, v0
	v_readfirstlane_b32 s3, v156
	v_lshl_add_u64 v[138:139], v[138:139], 0, s[8:9]
	s_mov_b32 m0, s3
	v_readfirstlane_b32 s3, v0
	global_load_lds_dwordx4 v[138:139], off
	v_lshl_add_u64 v[136:137], v[136:137], 0, s[8:9]
	s_mov_b32 m0, s3
	s_nop 0
	global_load_lds_dwordx4 v[136:137], off
	s_branch .LBB0_1153

; template <int EPI, int AMAP, int KOFFMODE, int K>
; __device__ __forceinline__ void gemm_phase(unsigned char* smem, const bf16_t* A, int lda, const bf16_t* Bt, int NT, const EpiArgs& ea) {
;     ...
;         for (int kt = 0; kt < nk; ++kt) {
;             if (kt + 1 < nk) GEMM_DMA(m0, n0, kt + 1, cur ^ 1);
;             else if (have_next) GEMM_DMA(m0n, n0n, 0, cur ^ 1);
;             const unsigned char* Ac = smem + cur * STGB + (wm * 128 + l31) * 128;
;             const unsigned char* Bc = smem + cur * STGB + 32768 + (wn * 64 + l31) * 128;
;             bf16x8 fa[2][4], fb[2][2];
;             fb[0][0] = *(const bf16x8*)(Bc + (((0) ^ yz) & 7) * 16);
;             fb[0][1] = *(const bf16x8*)(Bc + 32 * 128 + (((0) ^ yz) & 7) * 16);
; #pragma unroll
;             for (int i = 0; i < 4; ++i) fa[0][i] = *(const bf16x8*)(Ac + i * 32 * 128 + (((0) ^ yz) & 7) * 16);
; #pragma unroll
;             for (int s = 0; s < 4; ++s) {
;                 if (s < 3) {
;                     const int o_ = (((2 * (s + 1)) ^ yz) & 7) * 16;
;                     fb[(s + 1) & 1][0] = *(const bf16x8*)(Bc + o_);
;                     fb[(s + 1) & 1][1] = *(const bf16x8*)(Bc + 32 * 128 + o_);
; #pragma unroll
;                     for (int i = 0; i < 4; ++i) fa[(s + 1) & 1][i] = *(const bf16x8*)(Ac + i * 32 * 128 + o_);
;                 }
; #pragma unroll
;                 for (int i = 0; i < 4; ++i) {
;                     acc[i][0] = __builtin_amdgcn_mfma_f32_32x32x16_bf16(fa[s & 1][i], fb[s & 1][0], acc[i][0], 0, 0, 0);
;                     acc[i][1] = __builtin_amdgcn_mfma_f32_32x32x16_bf16(fa[s & 1][i], fb[s & 1][1], acc[i][1], 0, 0, 0);
;                 }
;                 __builtin_amdgcn_sched_barrier(0);
;             }
;             if (kt + 1 < nk) asm volatile("s_waitcnt vmcnt(0)" ::: "memory");
;             __builtin_amdgcn_s_barrier();
.LBB0_1429:
	s_mov_b32 s9, s13
	s_lshl_b32 s13, s9, 16
	s_xor_b32 s12, s13, 0x10000
	v_readfirstlane_b32 vcc_lo, v143
	s_nop 0
	s_add_u32 vcc_lo, vcc_lo, s12
	s_add_u32 s14, s4, 0xe380080
	s_addc_u32 s15, s5, 0
	s_mov_b32 m0, vcc_lo
	v_lshl_add_u64 v[164:165], v[136:137], 0, s[14:15]
	global_load_lds_dwordx4 v[164:165], off
	s_add_u32 s14, s4, 0xe3a0080
	s_addc_u32 s15, s5, 0
	s_add_u32 m0, vcc_lo, 0x2000
	v_lshl_add_u64 v[164:165], v[136:137], 0, s[14:15]
	global_load_lds_dwordx4 v[164:165], off
	s_add_u32 s14, s4, 0xe3c0080
	s_addc_u32 s15, s5, 0
	s_add_u32 m0, vcc_lo, 0x4000
	v_lshl_add_u64 v[164:165], v[136:137], 0, s[14:15]
	global_load_lds_dwordx4 v[164:165], off
	s_add_u32 s14, s4, 0xe3e0080
	s_addc_u32 s15, s5, 0
	s_add_u32 m0, vcc_lo, 0x6000
	v_lshl_add_u64 v[164:165], v[136:137], 0, s[14:15]
	global_load_lds_dwordx4 v[164:165], off
	s_add_u32 s14, s4, s20
	s_addc_u32 s15, s5, s21
	s_add_u32 m0, vcc_lo, 0x8000
	v_lshl_add_u64 v[164:165], v[138:139], 0, s[14:15]
	global_load_lds_dwordx4 v[164:165], off
	s_add_u32 s14, s4, 0x820080
	s_addc_u32 s15, s5, 0
	s_add_u32 m0, vcc_lo, 0xa000
	v_lshl_add_u64 v[164:165], v[138:139], 0, s[14:15]
	global_load_lds_dwordx4 v[164:165], off
	s_add_u32 s14, s4, s68
	s_addc_u32 s15, s5, s69
	s_add_u32 m0, vcc_lo, 0xc000
	v_lshl_add_u64 v[164:165], v[138:139], 0, s[14:15]
	global_load_lds_dwordx4 v[164:165], off
	s_add_u32 s14, s4, 0x860080
	s_addc_u32 s15, s5, 0
	s_add_u32 m0, vcc_lo, 0xe000
	v_lshl_add_u64 v[164:165], v[138:139], 0, s[14:15]
	global_load_lds_dwordx4 v[164:165], off
	v_add3_u32 v155, s13, v150, v149
	v_add_u32_e32 v155, v155, v152
	v_add3_u32 v0, s13, v147, v149
	v_add_u32_e32 v0, v0, v152
	ds_read_b128 v[208:211], v155 offset:32768
	ds_read_b128 v[212:215], v155 offset:36864
	s_waitcnt lgkmcnt(5)
	v_mfma_f32_32x32x16_bf16 v[114:129], v[192:195], v[156:159], v[114:129]
	v_mfma_f32_32x32x16_bf16 v[98:113], v[192:195], v[160:163], v[98:113]
	ds_read_b128 v[192:195], v0
	s_waitcnt lgkmcnt(5)
	v_mfma_f32_32x32x16_bf16 v[82:97], v[196:199], v[156:159], v[82:97]
	v_mfma_f32_32x32x16_bf16 v[66:81], v[196:199], v[160:163], v[66:81]
	ds_read_b128 v[196:199], v0 offset:4096
	s_waitcnt lgkmcnt(5)
	v_mfma_f32_32x32x16_bf16 v[50:65], v[200:203], v[156:159], v[50:65]
	v_mfma_f32_32x32x16_bf16 v[34:49], v[200:203], v[160:163], v[34:49]
	ds_read_b128 v[200:203], v0 offset:8192
	s_waitcnt lgkmcnt(5)
	v_mfma_f32_32x32x16_bf16 v[18:33], v[204:207], v[156:159], v[18:33]
	v_mfma_f32_32x32x16_bf16 v[2:17], v[204:207], v[160:163], v[2:17]
	ds_read_b128 v[204:207], v0 offset:12288
	v_add3_u32 v155, s13, v150, v149
	v_add_u32_e32 v155, v155, v153
	v_add3_u32 v0, s13, v147, v149
	v_add_u32_e32 v0, v0, v153
	ds_read_b128 v[156:159], v155 offset:32768
	ds_read_b128 v[160:163], v155 offset:36864
	s_waitcnt lgkmcnt(5)
	v_mfma_f32_32x32x16_bf16 v[114:129], v[192:195], v[208:211], v[114:129]
	v_mfma_f32_32x32x16_bf16 v[98:113], v[192:195], v[212:215], v[98:113]
	ds_read_b128 v[192:195], v0
	s_waitcnt lgkmcnt(5)
	v_mfma_f32_32x32x16_bf16 v[82:97], v[196:199], v[208:211], v[82:97]
	v_mfma_f32_32x32x16_bf16 v[66:81], v[196:199], v[212:215], v[66:81]
	ds_read_b128 v[196:199], v0 offset:4096
	s_waitcnt lgkmcnt(5)
	v_mfma_f32_32x32x16_bf16 v[50:65], v[200:203], v[208:211], v[50:65]
	v_mfma_f32_32x32x16_bf16 v[34:49], v[200:203], v[212:215], v[34:49]
	ds_read_b128 v[200:203], v0 offset:8192
	s_waitcnt lgkmcnt(5)
	v_mfma_f32_32x32x16_bf16 v[18:33], v[204:207], v[208:211], v[18:33]
	v_mfma_f32_32x32x16_bf16 v[2:17], v[204:207], v[212:215], v[2:17]
	ds_read_b128 v[204:207], v0 offset:12288
	v_add3_u32 v155, s13, v150, v149
	v_add_u32_e32 v155, v155, v154
	v_add3_u32 v0, s13, v147, v149
	v_add_u32_e32 v0, v0, v154
	ds_read_b128 v[208:211], v155 offset:32768
	ds_read_b128 v[212:215], v155 offset:36864
	s_waitcnt lgkmcnt(5)
	v_mfma_f32_32x32x16_bf16 v[114:129], v[192:195], v[156:159], v[114:129]
	v_mfma_f32_32x32x16_bf16 v[98:113], v[192:195], v[160:163], v[98:113]
	ds_read_b128 v[192:195], v0
	s_waitcnt lgkmcnt(5)
	v_mfma_f32_32x32x16_bf16 v[82:97], v[196:199], v[156:159], v[82:97]
	v_mfma_f32_32x32x16_bf16 v[66:81], v[196:199], v[160:163], v[66:81]
	ds_read_b128 v[196:199], v0 offset:4096
	s_waitcnt lgkmcnt(5)
	v_mfma_f32_32x32x16_bf16 v[50:65], v[200:203], v[156:159], v[50:65]
	v_mfma_f32_32x32x16_bf16 v[34:49], v[200:203], v[160:163], v[34:49]
	ds_read_b128 v[200:203], v0 offset:8192
	s_waitcnt lgkmcnt(5)
	v_mfma_f32_32x32x16_bf16 v[18:33], v[204:207], v[156:159], v[18:33]
	v_mfma_f32_32x32x16_bf16 v[2:17], v[204:207], v[160:163], v[2:17]
	ds_read_b128 v[204:207], v0 offset:12288
	s_waitcnt lgkmcnt(3)
	v_mfma_f32_32x32x16_bf16 v[114:129], v[192:195], v[208:211], v[114:129]
	v_mfma_f32_32x32x16_bf16 v[98:113], v[192:195], v[212:215], v[98:113]
	s_waitcnt lgkmcnt(2)
	v_mfma_f32_32x32x16_bf16 v[82:97], v[196:199], v[208:211], v[82:97]
	v_mfma_f32_32x32x16_bf16 v[66:81], v[196:199], v[212:215], v[66:81]
	s_waitcnt lgkmcnt(1)
	v_mfma_f32_32x32x16_bf16 v[50:65], v[200:203], v[208:211], v[50:65]
	v_mfma_f32_32x32x16_bf16 v[34:49], v[200:203], v[212:215], v[34:49]
	s_waitcnt lgkmcnt(0)
	s_waitcnt vmcnt(0)
	s_barrier
; template <int EPI, int AMAP, int KOFFMODE, int K>
; __device__ __forceinline__ void gemm_phase(unsigned char* smem, const bf16_t* A, int lda, const bf16_t* Bt, int NT, const EpiArgs& ea) {
;     ...
;             fb[0][0] = *(const bf16x8*)(Bc + (((0) ^ yz) & 7) * 16);
;             fb[0][1] = *(const bf16x8*)(Bc + 32 * 128 + (((0) ^ yz) & 7) * 16);
; #pragma unroll
;             for (int i = 0; i < 4; ++i) fa[0][i] = *(const bf16x8*)(Ac + i * 32 * 128 + (((0) ^ yz) & 7) * 16);
; #pragma unroll
;             for (int s = 0; s < 4; ++s) {
;                 if (s < 3) {
;                     const int o_ = (((2 * (s + 1)) ^ yz) & 7) * 16;
;                     fb[(s + 1) & 1][0] = *(const bf16x8*)(Bc + o_);
;                     fb[(s + 1) & 1][1] = *(const bf16x8*)(Bc + 32 * 128 + o_);
; #pragma unroll
;                     for (int i = 0; i < 4; ++i) fa[(s + 1) & 1][i] = *(const bf16x8*)(Ac + i * 32 * 128 + o_);
;                 }
; #pragma unroll
;                 for (int i = 0; i < 4; ++i) {
;                     acc[i][0] = __builtin_amdgcn_mfma_f32_32x32x16_bf16(fa[s & 1][i], fb[s & 1][0], acc[i][0], 0, 0, 0);
;                     acc[i][1] = __builtin_amdgcn_mfma_f32_32x32x16_bf16(fa[s & 1][i], fb[s & 1][1], acc[i][1], 0, 0, 0);
;                 }
;                 __builtin_amdgcn_sched_barrier(0);
;             }
;             if (kt + 1 < nk) asm volatile("s_waitcnt vmcnt(0)" ::: "memory");
;             __builtin_amdgcn_s_barrier();
;             cur ^= 1;
;         }
;         gemm_epilogue<EPI>(smem + (cur ^ 1) * STGB, acc, m0, n0, wm, wn, lane, ea);
;         ++rr; u = un; have = have_next; m0 = m0n; n0 = n0n;
	v_add3_u32 v155, s12, v150, v149
	v_add_u32_e32 v155, v155, v151
	v_add3_u32 v0, s12, v147, v149
	v_add_u32_e32 v0, v0, v151
	ds_read_b128 v[156:159], v155 offset:32768
	ds_read_b128 v[160:163], v155 offset:36864
	ds_read_b128 v[192:195], v0
	ds_read_b128 v[196:199], v0 offset:4096
	ds_read_b128 v[200:203], v0 offset:8192
	v_mfma_f32_32x32x16_bf16 v[18:33], v[204:207], v[208:211], v[18:33]
	v_mfma_f32_32x32x16_bf16 v[2:17], v[204:207], v[212:215], v[2:17]
	ds_read_b128 v[204:207], v0 offset:12288
	s_xor_b32 s13, s9, 1
	s_add_u32 s4, s4, 0x80
	s_addc_u32 s5, s5, 0
	s_cmpk_eq_i32 s4, 0x780
	s_cbranch_scc0 .LBB0_1429
	s_waitcnt lgkmcnt(0)
	s_andn2_b64 vcc, exec, s[2:3]
	s_lshl_b32 s2, s13, 16
	s_cbranch_vccnz .LBB0_1421
	v_add_u32_e32 v136, s8, v142
	s_xor_b32 s3, s2, 0x10000
	v_ashrrev_i32_e32 v137, 31, v136
	v_add_u32_e32 v138, s7, v142
	v_add_u32_e32 v0, s3, v143
	v_lshlrev_b64 v[136:137], 11, v[136:137]
	v_ashrrev_i32_e32 v139, 31, v138
	v_add_u32_e32 v155, 0x8000, v0
	v_readfirstlane_b32 s3, v0
	v_lshlrev_b64 v[138:139], 11, v[138:139]
	v_lshl_add_u64 v[136:137], v[130:131], 0, v[136:137]
	s_mov_b32 m0, s3
	v_readfirstlane_b32 s3, v155
	v_add_u32_e32 v155, 0x2000, v0
	v_lshl_add_u64 v[138:139], v[132:133], 0, v[138:139]
	global_load_lds_dwordx4 v[136:137], off
	s_mov_b32 m0, s3
	s_mov_b64 s[4:5], 0x20000
	v_readfirstlane_b32 s3, v155
	v_add_u32_e32 v155, 0xa000, v0
	global_load_lds_dwordx4 v[138:139], off
	v_lshl_add_u64 v[156:157], v[136:137], 0, s[4:5]
	s_mov_b32 m0, s3
	v_readfirstlane_b32 s3, v155
	v_add_u32_e32 v155, 0x4000, v0
	global_load_lds_dwordx4 v[156:157], off
	v_lshl_add_u64 v[156:157], v[138:139], 0, s[4:5]
	s_mov_b32 m0, s3
	s_mov_b64 s[4:5], 0x40000
	v_readfirstlane_b32 s3, v155
	v_add_u32_e32 v155, 0xc000, v0
	global_load_lds_dwordx4 v[156:157], off
	v_lshl_add_u64 v[156:157], v[136:137], 0, s[4:5]
	s_mov_b32 m0, s3
	v_readfirstlane_b32 s3, v155
	v_add_u32_e32 v155, 0x6000, v0
	global_load_lds_dwordx4 v[156:157], off
	v_lshl_add_u64 v[156:157], v[138:139], 0, s[4:5]
	s_mov_b32 m0, s3
	s_mov_b64 s[4:5], 0x60000
	v_readfirstlane_b32 s3, v155
	v_add_u32_e32 v0, 0xe000, v0
	global_load_lds_dwordx4 v[156:157], off
	v_lshl_add_u64 v[136:137], v[136:137], 0, s[4:5]
	s_mov_b32 m0, s3
	v_readfirstlane_b32 s3, v0
	global_load_lds_dwordx4 v[136:137], off
	v_lshl_add_u64 v[136:137], v[138:139], 0, s[4:5]
	s_mov_b32 m0, s3
	s_nop 0
	global_load_lds_dwordx4 v[136:137], off
	s_branch .LBB0_1421
